# v22 + SSD prompt unit: next-chunk prefetch waited at the next loop top (counted vmcnt) instead of before the output stage
# speedup vs baseline: 1.0102x; 1.0092x over previous
.LBB0_335:
	s_waitcnt vmcnt(0)
	v_readlane_b32 s0, v243, 0
	s_add_i32 s29, s29, s0
	s_add_i32 s61, s61, s0
	s_cmpk_lt_i32 s29, 0x100
	s_waitcnt lgkmcnt(0)
	s_barrier
	s_cbranch_scc0 .LBB0_378

.LBB0_350:
	s_waitcnt vmcnt(12)
	ds_write_b128 v129, v[6:9]
	ds_write_b128 v129, v[10:13] offset:34816
	ds_write_b128 v130, v[14:17]
	ds_write_b128 v130, v[18:21] offset:34816
	ds_write_b128 v129, v[26:29] offset:17408
	ds_write_b128 v129, v[30:33] offset:52224
	ds_write_b128 v131, v[34:37]
	ds_write_b128 v131, v[38:41] offset:34816
	ds_write_b128 v5, v[42:45]
	s_and_saveexec_b64 s[22:23], s[76:77]
	s_cbranch_execz .LBB0_352
	ds_write_b32 v123, v209
	ds_write_b32 v122, v210
	ds_write_b32 v85, v211

.LBB0_368:
	v_add_u32_e32 v218, v128, v132
	ds_read_b128 v[74:77], v218
	ds_read_b128 v[78:81], v218 offset:64
	s_waitcnt lgkmcnt(1)
	v_mfma_f32_16x16x32_bf16 v[74:77], v[66:69], v[74:77], 0
	s_waitcnt lgkmcnt(0)
	v_mfma_f32_16x16x32_bf16 v[74:77], v[62:65], v[78:81], v[74:77]
	ds_read_b128 v[78:81], v218 offset:128
	s_waitcnt lgkmcnt(0)
	v_mfma_f32_16x16x32_bf16 v[74:77], v[58:61], v[78:81], v[74:77]
	ds_read_b128 v[78:81], v218 offset:192
	s_waitcnt lgkmcnt(0)
	v_mfma_f32_16x16x32_bf16 v[74:77], v[70:73], v[78:81], v[74:77]
	ds_read_b128 v[78:81], v203
	s_waitcnt lgkmcnt(0)
	v_mfma_f32_16x16x32_bf16 v[66:69], v[66:69], v[78:81], 0
	ds_read_b128 v[78:81], v203 offset:64
	s_waitcnt lgkmcnt(0)
	v_mfma_f32_16x16x32_bf16 v[62:65], v[62:65], v[78:81], v[66:69]
	s_nop 4
	ds_read_b128 v[66:69], v203 offset:128
	s_waitcnt lgkmcnt(0)
	v_mfma_f32_16x16x32_bf16 v[58:61], v[58:61], v[66:69], v[62:65]
	s_nop 2
	ds_read_b128 v[62:65], v203 offset:192
	s_waitcnt vmcnt(9)
	s_waitcnt lgkmcnt(0)
	v_mfma_f32_16x16x32_bf16 v[58:61], v[70:73], v[62:65], v[58:61]
	v_and_b32_e32 v63, 64, v204
	v_xor_b32_e32 v62, 1, v204
	v_add_u32_e32 v63, 64, v63
	v_cmp_lt_i32_e32 vcc, v62, v63
	s_nop 1
	v_cndmask_b32_e32 v62, v204, v62, vcc
	v_lshlrev_b32_e32 v64, 2, v62
	v_xor_b32_e32 v62, 2, v204
	v_cmp_lt_i32_e32 vcc, v62, v63
	s_nop 1
	v_cndmask_b32_e32 v62, v204, v62, vcc
	v_lshlrev_b32_e32 v66, 2, v62
	v_xor_b32_e32 v62, 4, v204
	v_cmp_lt_i32_e32 vcc, v62, v63
	s_nop 1
	v_cndmask_b32_e32 v62, v204, v62, vcc
	v_lshlrev_b32_e32 v67, 2, v62
	v_xor_b32_e32 v62, 8, v204
	v_cmp_lt_i32_e32 vcc, v62, v63
	s_nop 1
	v_cndmask_b32_e32 v62, v204, v62, vcc
	v_lshlrev_b32_e32 v65, 2, v62
	ds_read_b32 v62, v166
	ds_read_u16 v68, v167
	ds_read_u16 v73, v167 offset:32
	s_waitcnt lgkmcnt(2)
	v_mul_f32_e32 v62, 0x3fb8aa3b, v62
	v_exp_f32_e32 v72, v62
	s_waitcnt lgkmcnt(1)
	v_lshlrev_b32_e32 v68, 16, v68
	v_add_u32_e32 v62, -3, v118
	v_ashrrev_i32_e32 v63, 31, v62
	v_fma_f32 v54, v74, v72, v54
	v_fmac_f32_e32 v54, v208, v68
	v_lshlrev_b32_e32 v68, 16, v217
	v_mul_f32_e32 v69, 0xbfb8aa3b, v68
	v_exp_f32_e32 v69, v69
	v_fma_f32 v50, v58, v72, v50
	v_lshlrev_b32_e32 v58, 16, v216
	v_add_f32_e32 v69, 1.0, v69
	v_rcp_f32_e32 v69, v69
	s_nop 0
	v_mul_f32_e32 v68, v69, v68
	v_mul_f32_e32 v54, v68, v54
	v_lshlrev_b64 v[68:69], 12, v[62:63]
	v_lshl_or_b32 v68, s94, 1, v68
	v_cvt_pk_bf16_f32 v74, v54, s0
	v_lshl_add_u64 v[70:71], v[98:99], 0, v[68:69]
	global_store_short v[70:71], v74, off
	s_waitcnt lgkmcnt(0)
	v_lshlrev_b32_e32 v70, 16, v73
	v_fmac_f32_e32 v50, v208, v70
	v_mul_f32_e32 v70, 0xbfb8aa3b, v58
	v_exp_f32_e32 v70, v70
	v_lshl_add_u64 v[68:69], v[116:117], 0, v[68:69]
	v_add_f32_e32 v70, 1.0, v70
	v_rcp_f32_e32 v70, v70
	s_nop 0
	v_mul_f32_e32 v58, v70, v58
	v_mul_f32_e32 v50, v58, v50
	v_mul_f32_e32 v58, v50, v50
	v_fmac_f32_e32 v58, v54, v54
	v_cvt_pk_bf16_f32 v50, v50, s0
	global_store_short v[68:69], v50, off
	ds_bpermute_b32 v50, v64, v58
	s_waitcnt lgkmcnt(0)
	v_add_f32_e32 v50, v58, v50
	ds_bpermute_b32 v54, v66, v50
	s_waitcnt lgkmcnt(0)
	v_add_f32_e32 v50, v50, v54
	ds_bpermute_b32 v54, v67, v50
	s_waitcnt lgkmcnt(0)
	v_add_f32_e32 v50, v50, v54
	ds_bpermute_b32 v54, v65, v50
	s_and_saveexec_b64 s[24:25], s[4:5]
	s_cbranch_execz .LBB0_370
	v_lshlrev_b64 v[62:63], 8, v[62:63]
	s_waitcnt lgkmcnt(0)
	v_add_f32_e32 v50, v50, v54
	v_lshl_add_u64 v[62:63], s[88:89], 0, v[62:63]
	global_store_dword v[62:63], v50, off
